# QKV V-tile epilogue: v_cvt_pk_bf16_f32 replaces manual bfe/add3 rounding plus v_perm packing (instruction selection)
# speedup vs baseline: 1.0082x; 1.0038x over previous
; template <int EPI>
; __device__ __forceinline__ void gemm_epilogue(KP P, f32x4 (&acc)[2][2][4][2], int brow, int bcol, int wr, int wc, int fr_, int fq_, const float* sRu) {
;     ...
;       float* fdst = prompt ? P->out + O_VP + (size_t)brow * 1024 + (bcol - 2048) : P->out + O_VS + (size_t)(brow - MP) * 1024 + (bcol - 2048);
;       bfu* vt = prompt ? (bfu*)(P->ws + WS_VTP) : (bfu*)(P->ws + WS_VTS);
; #pragma unroll
;       for (int ai = 0; ai < 2; ++ai)
; #pragma unroll
;         for (int m = 0; m < 4; ++m) {
;           __builtin_amdgcn_sched_barrier(0);
;           unsigned lr = lrow0 + ai * 128 + m * 16;
;           int row = brow + lr;
;           size_t tb;
;           unsigned tstr;
;           if (prompt) { tb = (size_t)(row >> 12) * 1024 * 4096 + (row & 4095); tstr = 4096; }
;           else { int rs = row - MP; tb = (size_t)(rs >> 6) * 1024 * SKV + 1024 + (rs & 63); tstr = SKV; }
; #pragma unroll
;           for (int bj = 0; bj < 2; ++bj)
; #pragma unroll
;             for (int n = 0; n < 2; ++n) {
;               f32x4 v = acc[ai][bj][m][n];
;               unsigned lc = lcol0 + bj * 128 + n * 16;
;               *(f32x4*)(fdst + lr * 1024 + lc) = v;
;               unsigned c = bcol - 2048 + lc;
; #pragma unroll
;               for (int j = 0; j < 4; ++j) vt[tb + (size_t)(c + j) * tstr] = f2bf(v[j]);
;             }
;         }
.LBB0_104:
	s_ashr_i32 s5, s4, 31
	s_and_b64 s[36:37], s[6:7], exec
	s_cselect_b32 s37, s5, 0
	s_cselect_b32 s36, s4, s60
	s_mov_b32 s5, 0x2128e000
	s_cselect_b32 s5, s5, 0x31cd6000
	s_lshl_b64 s[36:37], s[36:37], 12
	s_waitcnt lgkmcnt(0)
	s_add_u32 s9, s34, s36
	s_mov_b32 s43, s61
	s_addc_u32 s25, s35, s37
	s_lshl_b64 s[34:35], s[42:43], 2
	s_add_u32 s9, s9, s34
	s_addc_u32 s25, s25, s35
	s_add_u32 s34, s9, s5
	s_addc_u32 s35, s25, 0
	s_and_b64 s[36:37], s[6:7], exec
	s_mov_b32 s5, 0x1c598000
	s_cselect_b32 s5, s5, 0x25698000
	v_add_u32_e32 v0, 16, v157
	v_readlane_b32 s9, v241, 17
	s_add_u32 s36, s18, s5
	v_and_b32_e32 v187, 63, v0
	v_lshl_add_u32 v183, v158, 2, s9
	v_lshlrev_b32_e32 v0, 10, v150
	s_addc_u32 s37, s19, 0
	v_lshl_add_u64 v[144:145], v[0:1], 2, s[34:35]
	v_mov_b32_e32 v0, v183
	s_add_i32 s5, s42, 0xfffff800
	v_lshl_add_u64 v[188:189], v[130:131], 1, s[36:37]
	v_lshl_add_u64 v[130:131], v[0:1], 2, v[144:145]
	global_store_dwordx4 v[130:131], v[126:129], off
	v_add_u32_e32 v151, s5, v183
	v_add_u32_e32 v130, 16, v183
	v_mov_b32_e32 v131, v1
	v_lshl_add_u64 v[132:133], v[130:131], 2, v[144:145]
	global_store_dwordx4 v[132:133], v[122:125], off
	v_add_u32_e32 v160, s5, v130
	v_lshl_add_u64 v[222:223], v[188:189], 0, v[202:203]
	v_add_u32_e32 v204, v151, v196
	v_add_u32_e32 v205, v160, v196
	v_cvt_pk_bf16_f32 v212, v126, v127
	v_cvt_pk_bf16_f32 v228, v122, v123
	v_cvt_pk_bf16_f32 v213, v128, v129
	v_cvt_pk_bf16_f32 v229, v124, v125
	v_perm_b32 v214, v213, v212, v198
	v_perm_b32 v230, v229, v228, v198
	v_mad_u64_u32 v[208:209], s[38:39], s8, v204, 0
	v_mad_u64_u32 v[224:225], s[38:39], s8, v205, 0
	s_nop 0
	v_mov_b32_dpp v215, v214 quad_perm:[2,3,0,1] row_mask:0xf bank_mask:0xf
	v_mov_b32_dpp v231, v230 quad_perm:[2,3,0,1] row_mask:0xf bank_mask:0xf
	v_perm_b32 v216, v215, v212, v199
	v_perm_b32 v232, v231, v228, v199
	v_perm_b32 v217, v215, v213, v198
	v_perm_b32 v233, v231, v229, v198
	v_lshl_add_u64 v[208:209], v[208:209], 1, v[222:223]
	v_lshl_add_u64 v[224:225], v[224:225], 1, v[222:223]
	v_mov_b32_dpp v218, v216 quad_perm:[1,0,3,2] row_mask:0xf bank_mask:0xf
	v_mov_b32_dpp v234, v232 quad_perm:[1,0,3,2] row_mask:0xf bank_mask:0xf
	v_mov_b32_dpp v219, v217 quad_perm:[1,0,3,2] row_mask:0xf bank_mask:0xf
	v_mov_b32_dpp v235, v233 quad_perm:[1,0,3,2] row_mask:0xf bank_mask:0xf
	v_perm_b32 v220, v218, v216, v201
	v_perm_b32 v236, v234, v232, v201
	v_perm_b32 v221, v219, v217, v201
	v_perm_b32 v237, v235, v233, v201
	global_store_dwordx2 v[208:209], v[220:221], off
	global_store_dwordx2 v[224:225], v[236:237], off
	v_add_u32_e32 v132, 0x80, v183
	v_mov_b32_e32 v133, v1
	v_lshl_add_u64 v[142:143], v[132:133], 2, v[144:145]
	global_store_dwordx4 v[142:143], v[62:65], off
	v_add_u32_e32 v179, s5, v132
	v_add_u32_e32 v142, 0x90, v183
	v_mov_b32_e32 v143, v1
	v_lshl_add_u64 v[144:145], v[142:143], 2, v[144:145]
	global_store_dwordx4 v[144:145], v[58:61], off
	v_add_u32_e32 v183, s5, v142
	v_add_u32_e32 v206, v179, v196
	v_add_u32_e32 v207, v183, v196
	v_cvt_pk_bf16_f32 v212, v62, v63
	v_cvt_pk_bf16_f32 v228, v58, v59
	v_cvt_pk_bf16_f32 v213, v64, v65
	v_cvt_pk_bf16_f32 v229, v60, v61
	v_perm_b32 v214, v213, v212, v198
	v_perm_b32 v230, v229, v228, v198
	v_mad_u64_u32 v[208:209], s[38:39], s8, v206, 0
	v_mad_u64_u32 v[224:225], s[38:39], s8, v207, 0
	s_nop 0
	v_mov_b32_dpp v215, v214 quad_perm:[2,3,0,1] row_mask:0xf bank_mask:0xf
	v_mov_b32_dpp v231, v230 quad_perm:[2,3,0,1] row_mask:0xf bank_mask:0xf
	v_perm_b32 v216, v215, v212, v199
	v_perm_b32 v232, v231, v228, v199
	v_perm_b32 v217, v215, v213, v198
	v_perm_b32 v233, v231, v229, v198
	v_lshl_add_u64 v[208:209], v[208:209], 1, v[222:223]
	v_lshl_add_u64 v[224:225], v[224:225], 1, v[222:223]
	v_mov_b32_dpp v218, v216 quad_perm:[1,0,3,2] row_mask:0xf bank_mask:0xf
	v_mov_b32_dpp v234, v232 quad_perm:[1,0,3,2] row_mask:0xf bank_mask:0xf
	v_mov_b32_dpp v219, v217 quad_perm:[1,0,3,2] row_mask:0xf bank_mask:0xf
	v_mov_b32_dpp v235, v233 quad_perm:[1,0,3,2] row_mask:0xf bank_mask:0xf
	v_perm_b32 v220, v218, v216, v201
	v_perm_b32 v236, v234, v232, v201
	v_perm_b32 v221, v219, v217, v201
	v_perm_b32 v237, v235, v233, v201
	global_store_dwordx2 v[208:209], v[220:221], off
	global_store_dwordx2 v[224:225], v[236:237], off
	v_add_u32_e32 v189, 16, v150
	v_cndmask_b32_e64 v144, 0, 1, s[10:11]
	v_add_u32_e32 v188, s4, v189
	v_cmp_ne_u32_e64 s[8:9], 1, v144
	s_andn2_b64 vcc, exec, s[10:11]
	s_mov_b64 s[38:39], -1
	s_cbranch_vccnz .LBB0_106
	v_add_u32_e32 v144, 0xffff0000, v188
	v_ashrrev_i32_e32 v144, 6, v144
	s_mov_b32 s5, 0x110000
	v_mad_i64_i32 v[144:145], s[38:39], v144, s5, 0
	s_movk_i32 s5, 0x400
	v_or3_b32 v144, v144, v187, s5
	s_mov_b64 s[38:39], 0

; template <int EPI>
; __device__ __forceinline__ void gemm_epilogue(KP P, f32x4 (&acc)[2][2][4][2], int brow, int bcol, int wr, int wc, int fr_, int fq_, const float* sRu) {
;     ...
;       float* fdst = prompt ? P->out + O_VP + (size_t)brow * 1024 + (bcol - 2048) : P->out + O_VS + (size_t)(brow - MP) * 1024 + (bcol - 2048);
;       bfu* vt = prompt ? (bfu*)(P->ws + WS_VTP) : (bfu*)(P->ws + WS_VTS);
; #pragma unroll
;       for (int ai = 0; ai < 2; ++ai)
; #pragma unroll
;         for (int m = 0; m < 4; ++m) {
;           __builtin_amdgcn_sched_barrier(0);
;           unsigned lr = lrow0 + ai * 128 + m * 16;
;           int row = brow + lr;
;           size_t tb;
;           unsigned tstr;
;           if (prompt) { tb = (size_t)(row >> 12) * 1024 * 4096 + (row & 4095); tstr = 4096; }
;           else { int rs = row - MP; tb = (size_t)(rs >> 6) * 1024 * SKV + 1024 + (rs & 63); tstr = SKV; }
; #pragma unroll
;           for (int bj = 0; bj < 2; ++bj)
; #pragma unroll
;             for (int n = 0; n < 2; ++n) {
;               f32x4 v = acc[ai][bj][m][n];
;               unsigned lc = lcol0 + bj * 128 + n * 16;
;               *(f32x4*)(fdst + lr * 1024 + lc) = v;
;               unsigned c = bcol - 2048 + lc;
; #pragma unroll
;               for (int j = 0; j < 4; ++j) vt[tb + (size_t)(c + j) * tstr] = f2bf(v[j]);
;             }
;         }
.LBB0_108:
	v_lshlrev_b32_e32 v192, 10, v189
	v_mov_b32_e32 v193, v1
	v_lshl_add_u64 v[192:193], v[192:193], 2, s[34:35]
	v_lshl_add_u64 v[194:195], v[0:1], 2, v[192:193]
	v_lshl_add_u64 v[144:145], v[144:145], 1, s[36:37]
	global_store_dwordx4 v[194:195], v[118:121], off
	v_lshl_add_u64 v[194:195], v[130:131], 2, v[192:193]
	global_store_dwordx4 v[194:195], v[114:117], off
	v_lshl_add_u64 v[222:223], v[144:145], 0, v[202:203]
	v_cvt_pk_bf16_f32 v212, v118, v119
	v_cvt_pk_bf16_f32 v228, v114, v115
	v_cvt_pk_bf16_f32 v213, v120, v121
	v_cvt_pk_bf16_f32 v229, v116, v117
	v_perm_b32 v214, v213, v212, v198
	v_perm_b32 v230, v229, v228, v198
	v_mad_u64_u32 v[208:209], s[44:45], s38, v204, 0
	v_mad_u64_u32 v[224:225], s[44:45], s38, v205, 0
	s_nop 0
	v_mov_b32_dpp v215, v214 quad_perm:[2,3,0,1] row_mask:0xf bank_mask:0xf
	v_mov_b32_dpp v231, v230 quad_perm:[2,3,0,1] row_mask:0xf bank_mask:0xf
	v_perm_b32 v216, v215, v212, v199
	v_perm_b32 v232, v231, v228, v199
	v_perm_b32 v217, v215, v213, v198
	v_perm_b32 v233, v231, v229, v198
	v_lshl_add_u64 v[208:209], v[208:209], 1, v[222:223]
	v_lshl_add_u64 v[224:225], v[224:225], 1, v[222:223]
	v_mov_b32_dpp v218, v216 quad_perm:[1,0,3,2] row_mask:0xf bank_mask:0xf
	v_mov_b32_dpp v234, v232 quad_perm:[1,0,3,2] row_mask:0xf bank_mask:0xf
	v_mov_b32_dpp v219, v217 quad_perm:[1,0,3,2] row_mask:0xf bank_mask:0xf
	v_mov_b32_dpp v235, v233 quad_perm:[1,0,3,2] row_mask:0xf bank_mask:0xf
	v_perm_b32 v220, v218, v216, v201
	v_perm_b32 v236, v234, v232, v201
	v_perm_b32 v221, v219, v217, v201
	v_perm_b32 v237, v235, v233, v201
	global_store_dwordx2 v[208:209], v[220:221], off
	global_store_dwordx2 v[224:225], v[236:237], off
	v_lshl_add_u64 v[194:195], v[132:133], 2, v[192:193]
	global_store_dwordx4 v[194:195], v[54:57], off
	v_lshl_add_u64 v[192:193], v[142:143], 2, v[192:193]
	global_store_dwordx4 v[192:193], v[50:53], off
	v_xor_b32_e32 v188, 32, v190
	v_cvt_pk_bf16_f32 v212, v54, v55
	v_cvt_pk_bf16_f32 v228, v50, v51
	v_cvt_pk_bf16_f32 v213, v56, v57
	v_cvt_pk_bf16_f32 v229, v52, v53
	v_perm_b32 v214, v213, v212, v198
	v_perm_b32 v230, v229, v228, v198
	v_mad_u64_u32 v[208:209], s[44:45], s38, v206, 0
	v_mad_u64_u32 v[224:225], s[44:45], s38, v207, 0
	s_nop 0
	v_mov_b32_dpp v215, v214 quad_perm:[2,3,0,1] row_mask:0xf bank_mask:0xf
	v_mov_b32_dpp v231, v230 quad_perm:[2,3,0,1] row_mask:0xf bank_mask:0xf
	v_perm_b32 v216, v215, v212, v199
	v_perm_b32 v232, v231, v228, v199
	v_perm_b32 v217, v215, v213, v198
	v_perm_b32 v233, v231, v229, v198
	v_lshl_add_u64 v[208:209], v[208:209], 1, v[222:223]
	v_lshl_add_u64 v[224:225], v[224:225], 1, v[222:223]
	v_mov_b32_dpp v218, v216 quad_perm:[1,0,3,2] row_mask:0xf bank_mask:0xf
	v_mov_b32_dpp v234, v232 quad_perm:[1,0,3,2] row_mask:0xf bank_mask:0xf
	v_mov_b32_dpp v219, v217 quad_perm:[1,0,3,2] row_mask:0xf bank_mask:0xf
	v_mov_b32_dpp v235, v233 quad_perm:[1,0,3,2] row_mask:0xf bank_mask:0xf
	v_perm_b32 v220, v218, v216, v201
	v_perm_b32 v236, v234, v232, v201
	v_perm_b32 v221, v219, v217, v201
	v_perm_b32 v237, v235, v233, v201
	global_store_dwordx2 v[208:209], v[220:221], off
	global_store_dwordx2 v[224:225], v[236:237], off
	v_add_u32_e32 v191, 32, v150
	v_add_u32_e32 v189, s4, v191
	s_and_b64 vcc, exec, s[8:9]
	s_mov_b64 s[38:39], -1
	s_cbranch_vccnz .LBB0_110
	v_add_u32_e32 v144, 0xffff0000, v189
	v_ashrrev_i32_e32 v144, 6, v144
	s_mov_b32 s5, 0x110000
	v_mad_i64_i32 v[144:145], s[38:39], v144, s5, 0
	s_movk_i32 s5, 0x400
	v_or3_b32 v144, v144, v188, s5
	s_mov_b64 s[38:39], 0

; template <int EPI>
; __device__ __forceinline__ void gemm_epilogue(KP P, f32x4 (&acc)[2][2][4][2], int brow, int bcol, int wr, int wc, int fr_, int fq_, const float* sRu) {
;     ...
;       float* fdst = prompt ? P->out + O_VP + (size_t)brow * 1024 + (bcol - 2048) : P->out + O_VS + (size_t)(brow - MP) * 1024 + (bcol - 2048);
;       bfu* vt = prompt ? (bfu*)(P->ws + WS_VTP) : (bfu*)(P->ws + WS_VTS);
; #pragma unroll
;       for (int ai = 0; ai < 2; ++ai)
; #pragma unroll
;         for (int m = 0; m < 4; ++m) {
;           __builtin_amdgcn_sched_barrier(0);
;           unsigned lr = lrow0 + ai * 128 + m * 16;
;           int row = brow + lr;
;           size_t tb;
;           unsigned tstr;
;           if (prompt) { tb = (size_t)(row >> 12) * 1024 * 4096 + (row & 4095); tstr = 4096; }
;           else { int rs = row - MP; tb = (size_t)(rs >> 6) * 1024 * SKV + 1024 + (rs & 63); tstr = SKV; }
; #pragma unroll
;           for (int bj = 0; bj < 2; ++bj)
; #pragma unroll
;             for (int n = 0; n < 2; ++n) {
;               f32x4 v = acc[ai][bj][m][n];
;               unsigned lc = lcol0 + bj * 128 + n * 16;
;               *(f32x4*)(fdst + lr * 1024 + lc) = v;
;               unsigned c = bcol - 2048 + lc;
; #pragma unroll
;               for (int j = 0; j < 4; ++j) vt[tb + (size_t)(c + j) * tstr] = f2bf(v[j]);
;             }
;         }
.LBB0_112:
	v_lshlrev_b32_e32 v192, 10, v191
	v_mov_b32_e32 v193, v1
	v_lshl_add_u64 v[192:193], v[192:193], 2, s[34:35]
	v_lshl_add_u64 v[194:195], v[0:1], 2, v[192:193]
	v_lshl_add_u64 v[144:145], v[144:145], 1, s[36:37]
	global_store_dwordx4 v[194:195], v[110:113], off
	v_lshl_add_u64 v[194:195], v[130:131], 2, v[192:193]
	global_store_dwordx4 v[194:195], v[106:109], off
	v_lshl_add_u64 v[222:223], v[144:145], 0, v[202:203]
	v_cvt_pk_bf16_f32 v212, v110, v111
	v_cvt_pk_bf16_f32 v228, v106, v107
	v_cvt_pk_bf16_f32 v213, v112, v113
	v_cvt_pk_bf16_f32 v229, v108, v109
	v_perm_b32 v214, v213, v212, v198
	v_perm_b32 v230, v229, v228, v198
	v_mad_u64_u32 v[208:209], s[44:45], s38, v204, 0
	v_mad_u64_u32 v[224:225], s[44:45], s38, v205, 0
	s_nop 0
	v_mov_b32_dpp v215, v214 quad_perm:[2,3,0,1] row_mask:0xf bank_mask:0xf
	v_mov_b32_dpp v231, v230 quad_perm:[2,3,0,1] row_mask:0xf bank_mask:0xf
	v_perm_b32 v216, v215, v212, v199
	v_perm_b32 v232, v231, v228, v199
	v_perm_b32 v217, v215, v213, v198
	v_perm_b32 v233, v231, v229, v198
	v_lshl_add_u64 v[208:209], v[208:209], 1, v[222:223]
	v_lshl_add_u64 v[224:225], v[224:225], 1, v[222:223]
	v_mov_b32_dpp v218, v216 quad_perm:[1,0,3,2] row_mask:0xf bank_mask:0xf
	v_mov_b32_dpp v234, v232 quad_perm:[1,0,3,2] row_mask:0xf bank_mask:0xf
	v_mov_b32_dpp v219, v217 quad_perm:[1,0,3,2] row_mask:0xf bank_mask:0xf
	v_mov_b32_dpp v235, v233 quad_perm:[1,0,3,2] row_mask:0xf bank_mask:0xf
	v_perm_b32 v220, v218, v216, v201
	v_perm_b32 v236, v234, v232, v201
	v_perm_b32 v221, v219, v217, v201
	v_perm_b32 v237, v235, v233, v201
	global_store_dwordx2 v[208:209], v[220:221], off
	global_store_dwordx2 v[224:225], v[236:237], off
	v_lshl_add_u64 v[194:195], v[132:133], 2, v[192:193]
	global_store_dwordx4 v[194:195], v[46:49], off
	v_lshl_add_u64 v[192:193], v[142:143], 2, v[192:193]
	global_store_dwordx4 v[192:193], v[42:45], off
	v_add_u32_e32 v189, 48, v157
	v_and_b32_e32 v189, 63, v189
	v_cvt_pk_bf16_f32 v212, v46, v47
	v_cvt_pk_bf16_f32 v228, v42, v43
	v_cvt_pk_bf16_f32 v213, v48, v49
	v_cvt_pk_bf16_f32 v229, v44, v45
	v_perm_b32 v214, v213, v212, v198
	v_perm_b32 v230, v229, v228, v198
	v_mad_u64_u32 v[208:209], s[44:45], s38, v206, 0
	v_mad_u64_u32 v[224:225], s[44:45], s38, v207, 0
	s_nop 0
	v_mov_b32_dpp v215, v214 quad_perm:[2,3,0,1] row_mask:0xf bank_mask:0xf
	v_mov_b32_dpp v231, v230 quad_perm:[2,3,0,1] row_mask:0xf bank_mask:0xf
	v_perm_b32 v216, v215, v212, v199
	v_perm_b32 v232, v231, v228, v199
	v_perm_b32 v217, v215, v213, v198
	v_perm_b32 v233, v231, v229, v198
	v_lshl_add_u64 v[208:209], v[208:209], 1, v[222:223]
	v_lshl_add_u64 v[224:225], v[224:225], 1, v[222:223]
	v_mov_b32_dpp v218, v216 quad_perm:[1,0,3,2] row_mask:0xf bank_mask:0xf
	v_mov_b32_dpp v234, v232 quad_perm:[1,0,3,2] row_mask:0xf bank_mask:0xf
	v_mov_b32_dpp v219, v217 quad_perm:[1,0,3,2] row_mask:0xf bank_mask:0xf
	v_mov_b32_dpp v235, v233 quad_perm:[1,0,3,2] row_mask:0xf bank_mask:0xf
	v_perm_b32 v220, v218, v216, v201
	v_perm_b32 v236, v234, v232, v201
	v_perm_b32 v221, v219, v217, v201
	v_perm_b32 v237, v235, v233, v201
	global_store_dwordx2 v[208:209], v[220:221], off
	global_store_dwordx2 v[224:225], v[236:237], off
	v_add_u32_e32 v191, 48, v150
	v_add_u32_e32 v192, s4, v191
	s_and_b64 vcc, exec, s[8:9]
	s_mov_b64 s[38:39], -1
	s_cbranch_vccnz .LBB0_114
	v_add_u32_e32 v144, 0xffff0000, v192
	v_ashrrev_i32_e32 v144, 6, v144
	s_mov_b32 s5, 0x110000
	v_mad_i64_i32 v[144:145], s[38:39], v144, s5, 0
	s_movk_i32 s5, 0x400
	v_or3_b32 v144, v144, v189, s5
	s_mov_b64 s[38:39], 0

; template <int EPI>
; __device__ __forceinline__ void gemm_epilogue(KP P, f32x4 (&acc)[2][2][4][2], int brow, int bcol, int wr, int wc, int fr_, int fq_, const float* sRu) {
;     ...
;       float* fdst = prompt ? P->out + O_VP + (size_t)brow * 1024 + (bcol - 2048) : P->out + O_VS + (size_t)(brow - MP) * 1024 + (bcol - 2048);
;       bfu* vt = prompt ? (bfu*)(P->ws + WS_VTP) : (bfu*)(P->ws + WS_VTS);
; #pragma unroll
;       for (int ai = 0; ai < 2; ++ai)
; #pragma unroll
;         for (int m = 0; m < 4; ++m) {
;           __builtin_amdgcn_sched_barrier(0);
;           unsigned lr = lrow0 + ai * 128 + m * 16;
;           int row = brow + lr;
;           size_t tb;
;           unsigned tstr;
;           if (prompt) { tb = (size_t)(row >> 12) * 1024 * 4096 + (row & 4095); tstr = 4096; }
;           else { int rs = row - MP; tb = (size_t)(rs >> 6) * 1024 * SKV + 1024 + (rs & 63); tstr = SKV; }
; #pragma unroll
;           for (int bj = 0; bj < 2; ++bj)
; #pragma unroll
;             for (int n = 0; n < 2; ++n) {
;               f32x4 v = acc[ai][bj][m][n];
;               unsigned lc = lcol0 + bj * 128 + n * 16;
;               *(f32x4*)(fdst + lr * 1024 + lc) = v;
;               unsigned c = bcol - 2048 + lc;
; #pragma unroll
;               for (int j = 0; j < 4; ++j) vt[tb + (size_t)(c + j) * tstr] = f2bf(v[j]);
;             }
;         }
.LBB0_116:
	v_lshlrev_b32_e32 v192, 10, v191
	v_mov_b32_e32 v193, v1
	v_lshl_add_u64 v[192:193], v[192:193], 2, s[34:35]
	v_lshl_add_u64 v[194:195], v[0:1], 2, v[192:193]
	v_lshl_add_u64 v[144:145], v[144:145], 1, s[36:37]
	global_store_dwordx4 v[194:195], v[102:105], off
	v_lshl_add_u64 v[194:195], v[130:131], 2, v[192:193]
	global_store_dwordx4 v[194:195], v[98:101], off
	v_lshl_add_u64 v[222:223], v[144:145], 0, v[202:203]
	v_cvt_pk_bf16_f32 v212, v102, v103
	v_cvt_pk_bf16_f32 v228, v98, v99
	v_cvt_pk_bf16_f32 v213, v104, v105
	v_cvt_pk_bf16_f32 v229, v100, v101
	v_perm_b32 v214, v213, v212, v198
	v_perm_b32 v230, v229, v228, v198
	v_mad_u64_u32 v[208:209], s[44:45], s38, v204, 0
	v_mad_u64_u32 v[224:225], s[44:45], s38, v205, 0
	s_nop 0
	v_mov_b32_dpp v215, v214 quad_perm:[2,3,0,1] row_mask:0xf bank_mask:0xf
	v_mov_b32_dpp v231, v230 quad_perm:[2,3,0,1] row_mask:0xf bank_mask:0xf
	v_perm_b32 v216, v215, v212, v199
	v_perm_b32 v232, v231, v228, v199
	v_perm_b32 v217, v215, v213, v198
	v_perm_b32 v233, v231, v229, v198
	v_lshl_add_u64 v[208:209], v[208:209], 1, v[222:223]
	v_lshl_add_u64 v[224:225], v[224:225], 1, v[222:223]
	v_mov_b32_dpp v218, v216 quad_perm:[1,0,3,2] row_mask:0xf bank_mask:0xf
	v_mov_b32_dpp v234, v232 quad_perm:[1,0,3,2] row_mask:0xf bank_mask:0xf
	v_mov_b32_dpp v219, v217 quad_perm:[1,0,3,2] row_mask:0xf bank_mask:0xf
	v_mov_b32_dpp v235, v233 quad_perm:[1,0,3,2] row_mask:0xf bank_mask:0xf
	v_perm_b32 v220, v218, v216, v201
	v_perm_b32 v236, v234, v232, v201
	v_perm_b32 v221, v219, v217, v201
	v_perm_b32 v237, v235, v233, v201
	global_store_dwordx2 v[208:209], v[220:221], off
	global_store_dwordx2 v[224:225], v[236:237], off
	v_lshl_add_u64 v[194:195], v[132:133], 2, v[192:193]
	global_store_dwordx4 v[194:195], v[38:41], off
	v_lshl_add_u64 v[192:193], v[142:143], 2, v[192:193]
	global_store_dwordx4 v[192:193], v[34:37], off
	v_cvt_pk_bf16_f32 v212, v38, v39
	v_cvt_pk_bf16_f32 v228, v34, v35
	v_cvt_pk_bf16_f32 v213, v40, v41
	v_cvt_pk_bf16_f32 v229, v36, v37
	v_perm_b32 v214, v213, v212, v198
	v_perm_b32 v230, v229, v228, v198
	v_mad_u64_u32 v[208:209], s[44:45], s38, v206, 0
	v_mad_u64_u32 v[224:225], s[44:45], s38, v207, 0
	s_nop 0
	v_mov_b32_dpp v215, v214 quad_perm:[2,3,0,1] row_mask:0xf bank_mask:0xf
	v_mov_b32_dpp v231, v230 quad_perm:[2,3,0,1] row_mask:0xf bank_mask:0xf
	v_perm_b32 v216, v215, v212, v199
	v_perm_b32 v232, v231, v228, v199
	v_perm_b32 v217, v215, v213, v198
	v_perm_b32 v233, v231, v229, v198
	v_lshl_add_u64 v[208:209], v[208:209], 1, v[222:223]
	v_lshl_add_u64 v[224:225], v[224:225], 1, v[222:223]
	v_mov_b32_dpp v218, v216 quad_perm:[1,0,3,2] row_mask:0xf bank_mask:0xf
	v_mov_b32_dpp v234, v232 quad_perm:[1,0,3,2] row_mask:0xf bank_mask:0xf
	v_mov_b32_dpp v219, v217 quad_perm:[1,0,3,2] row_mask:0xf bank_mask:0xf
	v_mov_b32_dpp v235, v233 quad_perm:[1,0,3,2] row_mask:0xf bank_mask:0xf
	v_perm_b32 v220, v218, v216, v201
	v_perm_b32 v236, v234, v232, v201
	v_perm_b32 v221, v219, v217, v201
	v_perm_b32 v237, v235, v233, v201
	global_store_dwordx2 v[208:209], v[220:221], off
	global_store_dwordx2 v[224:225], v[236:237], off
	v_add_u32_e32 v191, 0x80, v150
	v_add_u32_e32 v192, s4, v191
	s_and_b64 vcc, exec, s[8:9]
	s_mov_b64 s[38:39], -1
	s_cbranch_vccnz .LBB0_118
	v_add_u32_e32 v144, 0xffff0000, v192
	v_ashrrev_i32_e32 v144, 6, v144
	s_mov_b32 s5, 0x110000
	v_mad_i64_i32 v[144:145], s[38:39], v144, s5, 0
	s_movk_i32 s5, 0x400
	v_or3_b32 v144, v144, v190, s5
	s_mov_b64 s[38:39], 0

; template <int EPI>
; __device__ __forceinline__ void gemm_epilogue(KP P, f32x4 (&acc)[2][2][4][2], int brow, int bcol, int wr, int wc, int fr_, int fq_, const float* sRu) {
;     ...
;       float* fdst = prompt ? P->out + O_VP + (size_t)brow * 1024 + (bcol - 2048) : P->out + O_VS + (size_t)(brow - MP) * 1024 + (bcol - 2048);
;       bfu* vt = prompt ? (bfu*)(P->ws + WS_VTP) : (bfu*)(P->ws + WS_VTS);
; #pragma unroll
;       for (int ai = 0; ai < 2; ++ai)
; #pragma unroll
;         for (int m = 0; m < 4; ++m) {
;           __builtin_amdgcn_sched_barrier(0);
;           unsigned lr = lrow0 + ai * 128 + m * 16;
;           int row = brow + lr;
;           size_t tb;
;           unsigned tstr;
;           if (prompt) { tb = (size_t)(row >> 12) * 1024 * 4096 + (row & 4095); tstr = 4096; }
;           else { int rs = row - MP; tb = (size_t)(rs >> 6) * 1024 * SKV + 1024 + (rs & 63); tstr = SKV; }
; #pragma unroll
;           for (int bj = 0; bj < 2; ++bj)
; #pragma unroll
;             for (int n = 0; n < 2; ++n) {
;               f32x4 v = acc[ai][bj][m][n];
;               unsigned lc = lcol0 + bj * 128 + n * 16;
;               *(f32x4*)(fdst + lr * 1024 + lc) = v;
;               unsigned c = bcol - 2048 + lc;
; #pragma unroll
;               for (int j = 0; j < 4; ++j) vt[tb + (size_t)(c + j) * tstr] = f2bf(v[j]);
;             }
;         }
.LBB0_120:
	v_lshlrev_b32_e32 v190, 10, v191
	v_mov_b32_e32 v191, v1
	v_lshl_add_u64 v[190:191], v[190:191], 2, s[34:35]
	v_lshl_add_u64 v[192:193], v[0:1], 2, v[190:191]
	global_store_dwordx4 v[192:193], v[94:97], off
	v_lshl_add_u64 v[144:145], v[144:145], 1, s[36:37]
	v_lshl_add_u64 v[192:193], v[130:131], 2, v[190:191]
	global_store_dwordx4 v[192:193], v[90:93], off
	v_lshl_add_u64 v[222:223], v[144:145], 0, v[202:203]
	v_cvt_pk_bf16_f32 v212, v94, v95
	v_cvt_pk_bf16_f32 v228, v90, v91
	v_cvt_pk_bf16_f32 v213, v96, v97
	v_cvt_pk_bf16_f32 v229, v92, v93
	v_perm_b32 v214, v213, v212, v198
	v_perm_b32 v230, v229, v228, v198
	v_mad_u64_u32 v[208:209], s[44:45], s38, v204, 0
	v_mad_u64_u32 v[224:225], s[44:45], s38, v205, 0
	s_nop 0
	v_mov_b32_dpp v215, v214 quad_perm:[2,3,0,1] row_mask:0xf bank_mask:0xf
	v_mov_b32_dpp v231, v230 quad_perm:[2,3,0,1] row_mask:0xf bank_mask:0xf
	v_perm_b32 v216, v215, v212, v199
	v_perm_b32 v232, v231, v228, v199
	v_perm_b32 v217, v215, v213, v198
	v_perm_b32 v233, v231, v229, v198
	v_lshl_add_u64 v[208:209], v[208:209], 1, v[222:223]
	v_lshl_add_u64 v[224:225], v[224:225], 1, v[222:223]
	v_mov_b32_dpp v218, v216 quad_perm:[1,0,3,2] row_mask:0xf bank_mask:0xf
	v_mov_b32_dpp v234, v232 quad_perm:[1,0,3,2] row_mask:0xf bank_mask:0xf
	v_mov_b32_dpp v219, v217 quad_perm:[1,0,3,2] row_mask:0xf bank_mask:0xf
	v_mov_b32_dpp v235, v233 quad_perm:[1,0,3,2] row_mask:0xf bank_mask:0xf
	v_perm_b32 v220, v218, v216, v201
	v_perm_b32 v236, v234, v232, v201
	v_perm_b32 v221, v219, v217, v201
	v_perm_b32 v237, v235, v233, v201
	global_store_dwordx2 v[208:209], v[220:221], off
	global_store_dwordx2 v[224:225], v[236:237], off
	v_lshl_add_u64 v[192:193], v[132:133], 2, v[190:191]
	global_store_dwordx4 v[192:193], v[30:33], off
	v_lshl_add_u64 v[190:191], v[142:143], 2, v[190:191]
	global_store_dwordx4 v[190:191], v[26:29], off
	v_cvt_pk_bf16_f32 v212, v30, v31
	v_cvt_pk_bf16_f32 v228, v26, v27
	v_cvt_pk_bf16_f32 v213, v32, v33
	v_cvt_pk_bf16_f32 v229, v28, v29
	v_perm_b32 v214, v213, v212, v198
	v_perm_b32 v230, v229, v228, v198
	v_mad_u64_u32 v[208:209], s[44:45], s38, v206, 0
	v_mad_u64_u32 v[224:225], s[44:45], s38, v207, 0
	s_nop 0
	v_mov_b32_dpp v215, v214 quad_perm:[2,3,0,1] row_mask:0xf bank_mask:0xf
	v_mov_b32_dpp v231, v230 quad_perm:[2,3,0,1] row_mask:0xf bank_mask:0xf
	v_perm_b32 v216, v215, v212, v199
	v_perm_b32 v232, v231, v228, v199
	v_perm_b32 v217, v215, v213, v198
	v_perm_b32 v233, v231, v229, v198
	v_lshl_add_u64 v[208:209], v[208:209], 1, v[222:223]
	v_lshl_add_u64 v[224:225], v[224:225], 1, v[222:223]
	v_mov_b32_dpp v218, v216 quad_perm:[1,0,3,2] row_mask:0xf bank_mask:0xf
	v_mov_b32_dpp v234, v232 quad_perm:[1,0,3,2] row_mask:0xf bank_mask:0xf
	v_mov_b32_dpp v219, v217 quad_perm:[1,0,3,2] row_mask:0xf bank_mask:0xf
	v_mov_b32_dpp v235, v233 quad_perm:[1,0,3,2] row_mask:0xf bank_mask:0xf
	v_perm_b32 v220, v218, v216, v201
	v_perm_b32 v236, v234, v232, v201
	v_perm_b32 v221, v219, v217, v201
	v_perm_b32 v237, v235, v233, v201
	global_store_dwordx2 v[208:209], v[220:221], off
	global_store_dwordx2 v[224:225], v[236:237], off
	v_add_u32_e32 v190, 0x90, v150
	v_add_u32_e32 v191, s4, v190
	s_and_b64 vcc, exec, s[8:9]
	s_mov_b64 s[38:39], -1
	s_cbranch_vccnz .LBB0_122
	v_add_u32_e32 v144, 0xffff0000, v191
	v_ashrrev_i32_e32 v144, 6, v144
	s_mov_b32 s5, 0x110000
	v_mad_i64_i32 v[144:145], s[38:39], v144, s5, 0
	s_movk_i32 s5, 0x400
	v_or3_b32 v144, v144, v187, s5
	s_mov_b64 s[38:39], 0

; template <int EPI>
; __device__ __forceinline__ void gemm_epilogue(KP P, f32x4 (&acc)[2][2][4][2], int brow, int bcol, int wr, int wc, int fr_, int fq_, const float* sRu) {
;     ...
;       float* fdst = prompt ? P->out + O_VP + (size_t)brow * 1024 + (bcol - 2048) : P->out + O_VS + (size_t)(brow - MP) * 1024 + (bcol - 2048);
;       bfu* vt = prompt ? (bfu*)(P->ws + WS_VTP) : (bfu*)(P->ws + WS_VTS);
; #pragma unroll
;       for (int ai = 0; ai < 2; ++ai)
; #pragma unroll
;         for (int m = 0; m < 4; ++m) {
;           __builtin_amdgcn_sched_barrier(0);
;           unsigned lr = lrow0 + ai * 128 + m * 16;
;           int row = brow + lr;
;           size_t tb;
;           unsigned tstr;
;           if (prompt) { tb = (size_t)(row >> 12) * 1024 * 4096 + (row & 4095); tstr = 4096; }
;           else { int rs = row - MP; tb = (size_t)(rs >> 6) * 1024 * SKV + 1024 + (rs & 63); tstr = SKV; }
; #pragma unroll
;           for (int bj = 0; bj < 2; ++bj)
; #pragma unroll
;             for (int n = 0; n < 2; ++n) {
;               f32x4 v = acc[ai][bj][m][n];
;               unsigned lc = lcol0 + bj * 128 + n * 16;
;               *(f32x4*)(fdst + lr * 1024 + lc) = v;
;               unsigned c = bcol - 2048 + lc;
; #pragma unroll
;               for (int j = 0; j < 4; ++j) vt[tb + (size_t)(c + j) * tstr] = f2bf(v[j]);
;             }
;         }
.LBB0_124:
	v_lshlrev_b32_e32 v190, 10, v190
	v_mov_b32_e32 v191, v1
	v_lshl_add_u64 v[190:191], v[190:191], 2, s[34:35]
	v_lshl_add_u64 v[192:193], v[0:1], 2, v[190:191]
	v_lshl_add_u64 v[144:145], v[144:145], 1, s[36:37]
	global_store_dwordx4 v[192:193], v[86:89], off
	v_lshl_add_u64 v[192:193], v[130:131], 2, v[190:191]
	global_store_dwordx4 v[192:193], v[82:85], off
	v_lshl_add_u64 v[222:223], v[144:145], 0, v[202:203]
	v_cvt_pk_bf16_f32 v212, v86, v87
	v_cvt_pk_bf16_f32 v228, v82, v83
	v_cvt_pk_bf16_f32 v213, v88, v89
	v_cvt_pk_bf16_f32 v229, v84, v85
	v_perm_b32 v214, v213, v212, v198
	v_perm_b32 v230, v229, v228, v198
	v_mad_u64_u32 v[208:209], s[44:45], s38, v204, 0
	v_mad_u64_u32 v[224:225], s[44:45], s38, v205, 0
	s_nop 0
	v_mov_b32_dpp v215, v214 quad_perm:[2,3,0,1] row_mask:0xf bank_mask:0xf
	v_mov_b32_dpp v231, v230 quad_perm:[2,3,0,1] row_mask:0xf bank_mask:0xf
	v_perm_b32 v216, v215, v212, v199
	v_perm_b32 v232, v231, v228, v199
	v_perm_b32 v217, v215, v213, v198
	v_perm_b32 v233, v231, v229, v198
	v_lshl_add_u64 v[208:209], v[208:209], 1, v[222:223]
	v_lshl_add_u64 v[224:225], v[224:225], 1, v[222:223]
	v_mov_b32_dpp v218, v216 quad_perm:[1,0,3,2] row_mask:0xf bank_mask:0xf
	v_mov_b32_dpp v234, v232 quad_perm:[1,0,3,2] row_mask:0xf bank_mask:0xf
	v_mov_b32_dpp v219, v217 quad_perm:[1,0,3,2] row_mask:0xf bank_mask:0xf
	v_mov_b32_dpp v235, v233 quad_perm:[1,0,3,2] row_mask:0xf bank_mask:0xf
	v_perm_b32 v220, v218, v216, v201
	v_perm_b32 v236, v234, v232, v201
	v_perm_b32 v221, v219, v217, v201
	v_perm_b32 v237, v235, v233, v201
	global_store_dwordx2 v[208:209], v[220:221], off
	global_store_dwordx2 v[224:225], v[236:237], off
	v_lshl_add_u64 v[192:193], v[132:133], 2, v[190:191]
	global_store_dwordx4 v[192:193], v[22:25], off
	v_lshl_add_u64 v[190:191], v[142:143], 2, v[190:191]
	global_store_dwordx4 v[190:191], v[18:21], off
	v_cvt_pk_bf16_f32 v212, v22, v23
	v_cvt_pk_bf16_f32 v228, v18, v19
	v_cvt_pk_bf16_f32 v213, v24, v25
	v_cvt_pk_bf16_f32 v229, v20, v21
	v_perm_b32 v214, v213, v212, v198
	v_perm_b32 v230, v229, v228, v198
	v_mad_u64_u32 v[208:209], s[44:45], s38, v206, 0
	v_mad_u64_u32 v[224:225], s[44:45], s38, v207, 0
	s_nop 0
	v_mov_b32_dpp v215, v214 quad_perm:[2,3,0,1] row_mask:0xf bank_mask:0xf
	v_mov_b32_dpp v231, v230 quad_perm:[2,3,0,1] row_mask:0xf bank_mask:0xf
	v_perm_b32 v216, v215, v212, v199
	v_perm_b32 v232, v231, v228, v199
	v_perm_b32 v217, v215, v213, v198
	v_perm_b32 v233, v231, v229, v198
	v_lshl_add_u64 v[208:209], v[208:209], 1, v[222:223]
	v_lshl_add_u64 v[224:225], v[224:225], 1, v[222:223]
	v_mov_b32_dpp v218, v216 quad_perm:[1,0,3,2] row_mask:0xf bank_mask:0xf
	v_mov_b32_dpp v234, v232 quad_perm:[1,0,3,2] row_mask:0xf bank_mask:0xf
	v_mov_b32_dpp v219, v217 quad_perm:[1,0,3,2] row_mask:0xf bank_mask:0xf
	v_mov_b32_dpp v235, v233 quad_perm:[1,0,3,2] row_mask:0xf bank_mask:0xf
	v_perm_b32 v220, v218, v216, v201
	v_perm_b32 v236, v234, v232, v201
	v_perm_b32 v221, v219, v217, v201
	v_perm_b32 v237, v235, v233, v201
	global_store_dwordx2 v[208:209], v[220:221], off
	global_store_dwordx2 v[224:225], v[236:237], off
	v_add_u32_e32 v187, 0xa0, v150
	v_add_u32_e32 v190, s4, v187
	s_and_b64 vcc, exec, s[8:9]
	s_mov_b64 s[38:39], -1
	s_cbranch_vccnz .LBB0_126
	v_add_u32_e32 v144, 0xffff0000, v190
	v_ashrrev_i32_e32 v144, 6, v144
	s_mov_b32 s5, 0x110000
	v_mad_i64_i32 v[144:145], s[38:39], v144, s5, 0
	s_movk_i32 s5, 0x400
	v_or3_b32 v144, v144, v188, s5
	s_mov_b64 s[38:39], 0

; template <int EPI>
; __device__ __forceinline__ void gemm_epilogue(KP P, f32x4 (&acc)[2][2][4][2], int brow, int bcol, int wr, int wc, int fr_, int fq_, const float* sRu) {
;     ...
;       float* fdst = prompt ? P->out + O_VP + (size_t)brow * 1024 + (bcol - 2048) : P->out + O_VS + (size_t)(brow - MP) * 1024 + (bcol - 2048);
;       bfu* vt = prompt ? (bfu*)(P->ws + WS_VTP) : (bfu*)(P->ws + WS_VTS);
; #pragma unroll
;       for (int ai = 0; ai < 2; ++ai)
; #pragma unroll
;         for (int m = 0; m < 4; ++m) {
;           __builtin_amdgcn_sched_barrier(0);
;           unsigned lr = lrow0 + ai * 128 + m * 16;
;           int row = brow + lr;
;           size_t tb;
;           unsigned tstr;
;           if (prompt) { tb = (size_t)(row >> 12) * 1024 * 4096 + (row & 4095); tstr = 4096; }
;           else { int rs = row - MP; tb = (size_t)(rs >> 6) * 1024 * SKV + 1024 + (rs & 63); tstr = SKV; }
; #pragma unroll
;           for (int bj = 0; bj < 2; ++bj)
; #pragma unroll
;             for (int n = 0; n < 2; ++n) {
;               f32x4 v = acc[ai][bj][m][n];
;               unsigned lc = lcol0 + bj * 128 + n * 16;
;               *(f32x4*)(fdst + lr * 1024 + lc) = v;
;               unsigned c = bcol - 2048 + lc;
; #pragma unroll
;               for (int j = 0; j < 4; ++j) vt[tb + (size_t)(c + j) * tstr] = f2bf(v[j]);
;             }
;         }
.LBB0_128:
	v_lshlrev_b32_e32 v190, 10, v187
	v_mov_b32_e32 v191, v1
	v_lshl_add_u64 v[190:191], v[190:191], 2, s[34:35]
	v_lshl_add_u64 v[192:193], v[0:1], 2, v[190:191]
	v_lshl_add_u64 v[144:145], v[144:145], 1, s[36:37]
	global_store_dwordx4 v[192:193], v[78:81], off
	v_lshl_add_u64 v[192:193], v[130:131], 2, v[190:191]
	global_store_dwordx4 v[192:193], v[74:77], off
	v_lshl_add_u64 v[222:223], v[144:145], 0, v[202:203]
	v_cvt_pk_bf16_f32 v212, v78, v79
	v_cvt_pk_bf16_f32 v228, v74, v75
	v_cvt_pk_bf16_f32 v213, v80, v81
	v_cvt_pk_bf16_f32 v229, v76, v77
	v_perm_b32 v214, v213, v212, v198
	v_perm_b32 v230, v229, v228, v198
	v_mad_u64_u32 v[208:209], s[44:45], s38, v204, 0
	v_mad_u64_u32 v[224:225], s[44:45], s38, v205, 0
	s_nop 0
	v_mov_b32_dpp v215, v214 quad_perm:[2,3,0,1] row_mask:0xf bank_mask:0xf
	v_mov_b32_dpp v231, v230 quad_perm:[2,3,0,1] row_mask:0xf bank_mask:0xf
	v_perm_b32 v216, v215, v212, v199
	v_perm_b32 v232, v231, v228, v199
	v_perm_b32 v217, v215, v213, v198
	v_perm_b32 v233, v231, v229, v198
	v_lshl_add_u64 v[208:209], v[208:209], 1, v[222:223]
	v_lshl_add_u64 v[224:225], v[224:225], 1, v[222:223]
	v_mov_b32_dpp v218, v216 quad_perm:[1,0,3,2] row_mask:0xf bank_mask:0xf
	v_mov_b32_dpp v234, v232 quad_perm:[1,0,3,2] row_mask:0xf bank_mask:0xf
	v_mov_b32_dpp v219, v217 quad_perm:[1,0,3,2] row_mask:0xf bank_mask:0xf
	v_mov_b32_dpp v235, v233 quad_perm:[1,0,3,2] row_mask:0xf bank_mask:0xf
	v_perm_b32 v220, v218, v216, v201
	v_perm_b32 v236, v234, v232, v201
	v_perm_b32 v221, v219, v217, v201
	v_perm_b32 v237, v235, v233, v201
	global_store_dwordx2 v[208:209], v[220:221], off
	global_store_dwordx2 v[224:225], v[236:237], off
	v_lshl_add_u64 v[192:193], v[132:133], 2, v[190:191]
	global_store_dwordx4 v[192:193], v[14:17], off
	v_lshl_add_u64 v[190:191], v[142:143], 2, v[190:191]
	global_store_dwordx4 v[190:191], v[10:13], off
	v_cvt_pk_bf16_f32 v212, v14, v15
	v_cvt_pk_bf16_f32 v228, v10, v11
	v_cvt_pk_bf16_f32 v213, v16, v17
	v_cvt_pk_bf16_f32 v229, v12, v13
	v_perm_b32 v214, v213, v212, v198
	v_perm_b32 v230, v229, v228, v198
	v_mad_u64_u32 v[208:209], s[44:45], s38, v206, 0
	v_mad_u64_u32 v[224:225], s[44:45], s38, v207, 0
	s_nop 0
	v_mov_b32_dpp v215, v214 quad_perm:[2,3,0,1] row_mask:0xf bank_mask:0xf
	v_mov_b32_dpp v231, v230 quad_perm:[2,3,0,1] row_mask:0xf bank_mask:0xf
	v_perm_b32 v216, v215, v212, v199
	v_perm_b32 v232, v231, v228, v199
	v_perm_b32 v217, v215, v213, v198
	v_perm_b32 v233, v231, v229, v198
	v_lshl_add_u64 v[208:209], v[208:209], 1, v[222:223]
	v_lshl_add_u64 v[224:225], v[224:225], 1, v[222:223]
	v_mov_b32_dpp v218, v216 quad_perm:[1,0,3,2] row_mask:0xf bank_mask:0xf
	v_mov_b32_dpp v234, v232 quad_perm:[1,0,3,2] row_mask:0xf bank_mask:0xf
	v_mov_b32_dpp v219, v217 quad_perm:[1,0,3,2] row_mask:0xf bank_mask:0xf
	v_mov_b32_dpp v235, v233 quad_perm:[1,0,3,2] row_mask:0xf bank_mask:0xf
	v_perm_b32 v220, v218, v216, v201
	v_perm_b32 v236, v234, v232, v201
	v_perm_b32 v221, v219, v217, v201
	v_perm_b32 v237, v235, v233, v201
	global_store_dwordx2 v[208:209], v[220:221], off
	global_store_dwordx2 v[224:225], v[236:237], off
	v_add_u32_e32 v150, 0xb0, v150
	v_add_u32_e32 v187, s4, v150
	s_and_b64 vcc, exec, s[8:9]
	s_mov_b64 s[8:9], -1
	s_cbranch_vccnz .LBB0_130
	v_add_u32_e32 v144, 0xffff0000, v187
	v_ashrrev_i32_e32 v144, 6, v144
	s_mov_b32 s5, 0x110000
	v_mad_i64_i32 v[144:145], s[8:9], v144, s5, 0
	s_movk_i32 s5, 0x400
	v_or3_b32 v144, v144, v189, s5
	s_mov_b64 s[8:9], 0

; template <int EPI>
; __device__ __forceinline__ void gemm_epilogue(KP P, f32x4 (&acc)[2][2][4][2], int brow, int bcol, int wr, int wc, int fr_, int fq_, const float* sRu) {
;     ...
;       float* fdst = prompt ? P->out + O_VP + (size_t)brow * 1024 + (bcol - 2048) : P->out + O_VS + (size_t)(brow - MP) * 1024 + (bcol - 2048);
;       bfu* vt = prompt ? (bfu*)(P->ws + WS_VTP) : (bfu*)(P->ws + WS_VTS);
; #pragma unroll
;       for (int ai = 0; ai < 2; ++ai)
; #pragma unroll
;         for (int m = 0; m < 4; ++m) {
;           __builtin_amdgcn_sched_barrier(0);
;           unsigned lr = lrow0 + ai * 128 + m * 16;
;           int row = brow + lr;
;           size_t tb;
;           unsigned tstr;
;           if (prompt) { tb = (size_t)(row >> 12) * 1024 * 4096 + (row & 4095); tstr = 4096; }
;           else { int rs = row - MP; tb = (size_t)(rs >> 6) * 1024 * SKV + 1024 + (rs & 63); tstr = SKV; }
; #pragma unroll
;           for (int bj = 0; bj < 2; ++bj)
; #pragma unroll
;             for (int n = 0; n < 2; ++n) {
;               f32x4 v = acc[ai][bj][m][n];
;               unsigned lc = lcol0 + bj * 128 + n * 16;
;               *(f32x4*)(fdst + lr * 1024 + lc) = v;
;               unsigned c = bcol - 2048 + lc;
; #pragma unroll
;               for (int j = 0; j < 4; ++j) vt[tb + (size_t)(c + j) * tstr] = f2bf(v[j]);
;             }
;         }
.LBB0_132:
	v_lshlrev_b32_e32 v188, 10, v150
	v_mov_b32_e32 v189, v1
	v_lshl_add_u64 v[188:189], v[188:189], 2, s[34:35]
	v_lshl_add_u64 v[144:145], v[144:145], 1, s[36:37]
	v_lshl_add_u64 v[190:191], v[0:1], 2, v[188:189]
	global_store_dwordx4 v[190:191], v[70:73], off
	v_lshl_add_u64 v[130:131], v[130:131], 2, v[188:189]
	global_store_dwordx4 v[130:131], v[66:69], off
	v_lshl_add_u64 v[222:223], v[144:145], 0, v[202:203]
	v_cvt_pk_bf16_f32 v212, v70, v71
	v_cvt_pk_bf16_f32 v228, v66, v67
	v_cvt_pk_bf16_f32 v213, v72, v73
	v_cvt_pk_bf16_f32 v229, v68, v69
	v_perm_b32 v214, v213, v212, v198
	v_perm_b32 v230, v229, v228, v198
	v_mad_u64_u32 v[208:209], s[34:35], s8, v204, 0
	v_mad_u64_u32 v[224:225], s[34:35], s8, v205, 0
	s_nop 0
	v_mov_b32_dpp v215, v214 quad_perm:[2,3,0,1] row_mask:0xf bank_mask:0xf
	v_mov_b32_dpp v231, v230 quad_perm:[2,3,0,1] row_mask:0xf bank_mask:0xf
	v_perm_b32 v216, v215, v212, v199
	v_perm_b32 v232, v231, v228, v199
	v_perm_b32 v217, v215, v213, v198
	v_perm_b32 v233, v231, v229, v198
	v_lshl_add_u64 v[208:209], v[208:209], 1, v[222:223]
	v_lshl_add_u64 v[224:225], v[224:225], 1, v[222:223]
	v_mov_b32_dpp v218, v216 quad_perm:[1,0,3,2] row_mask:0xf bank_mask:0xf
	v_mov_b32_dpp v234, v232 quad_perm:[1,0,3,2] row_mask:0xf bank_mask:0xf
	v_mov_b32_dpp v219, v217 quad_perm:[1,0,3,2] row_mask:0xf bank_mask:0xf
	v_mov_b32_dpp v235, v233 quad_perm:[1,0,3,2] row_mask:0xf bank_mask:0xf
	v_perm_b32 v220, v218, v216, v201
	v_perm_b32 v236, v234, v232, v201
	v_perm_b32 v221, v219, v217, v201
	v_perm_b32 v237, v235, v233, v201
	global_store_dwordx2 v[208:209], v[220:221], off
	global_store_dwordx2 v[224:225], v[236:237], off
	v_lshl_add_u64 v[130:131], v[132:133], 2, v[188:189]
	global_store_dwordx4 v[130:131], v[6:9], off
	v_lshl_add_u64 v[130:131], v[142:143], 2, v[188:189]
	global_store_dwordx4 v[130:131], v[2:5], off
	v_cvt_pk_bf16_f32 v212, v6, v7
	v_cvt_pk_bf16_f32 v228, v2, v3
	v_cvt_pk_bf16_f32 v213, v8, v9
	v_cvt_pk_bf16_f32 v229, v4, v5
	v_perm_b32 v214, v213, v212, v198
	v_perm_b32 v230, v229, v228, v198
	v_mad_u64_u32 v[208:209], s[34:35], s8, v206, 0
	v_mad_u64_u32 v[224:225], s[34:35], s8, v207, 0
	s_nop 0
	v_mov_b32_dpp v215, v214 quad_perm:[2,3,0,1] row_mask:0xf bank_mask:0xf
	v_mov_b32_dpp v231, v230 quad_perm:[2,3,0,1] row_mask:0xf bank_mask:0xf
	v_perm_b32 v216, v215, v212, v199
	v_perm_b32 v232, v231, v228, v199
	v_perm_b32 v217, v215, v213, v198
	v_perm_b32 v233, v231, v229, v198
	v_lshl_add_u64 v[208:209], v[208:209], 1, v[222:223]
	v_lshl_add_u64 v[224:225], v[224:225], 1, v[222:223]
	v_mov_b32_dpp v218, v216 quad_perm:[1,0,3,2] row_mask:0xf bank_mask:0xf
	v_mov_b32_dpp v234, v232 quad_perm:[1,0,3,2] row_mask:0xf bank_mask:0xf
	v_mov_b32_dpp v219, v217 quad_perm:[1,0,3,2] row_mask:0xf bank_mask:0xf
	v_mov_b32_dpp v235, v233 quad_perm:[1,0,3,2] row_mask:0xf bank_mask:0xf
	v_perm_b32 v220, v218, v216, v201
	v_perm_b32 v236, v234, v232, v201
	v_perm_b32 v221, v219, v217, v201
	v_perm_b32 v237, v235, v233, v201
	global_store_dwordx2 v[208:209], v[220:221], off
	global_store_dwordx2 v[224:225], v[236:237], off
	s_mov_b64 s[8:9], 0
